# modulate (XCD-aligned loop): x rows of the next item prefetched into shadow registers behind the parameter loads; parameter loads hoisted, row 1 reuses row 0 parameters
# speedup vs baseline: 1.1529x; 1.0068x over previous
.LBB0_906:
	v_lshlrev_b32_e32 v0, 3, v175
	v_and_b32_e32 v34, 0x1f8, v0
	v_lshlrev_b32_e32 v0, 2, v34
	v_readfirstlane_b32 s13, v175
	s_ashr_i32 s13, s13, 5
	s_and_b32 s13, s13, -2
	s_add_i32 s26, s22, s13
	s_cmpk_gt_i32 s26, 0x3fff
	s_cselect_b32 s14, s19, s21
	s_cselect_b32 s15, s18, s20
	s_cselect_b32 s100, 0x4000, 0
	s_sub_i32 s100, s26, s100
	s_lshr_b32 s101, s100, 20
	s_lshl_b32 s100, s100, 12
	s_add_u32 s14, s14, s100
	s_addc_u32 s15, s15, s101
	global_load_dwordx4 v[176:179], v0, s[14:15]
	global_load_dwordx4 v[180:183], v0, s[14:15] offset:16
	global_load_dwordx4 v[184:187], v0, s[14:15] offset:2048
	global_load_dwordx4 v[188:191], v0, s[14:15] offset:2064
	s_add_i32 s26, s26, 1
	s_cmpk_gt_i32 s26, 0x3fff
	s_cselect_b32 s14, s19, s21
	s_cselect_b32 s15, s18, s20
	s_cselect_b32 s100, 0x4000, 0
	s_sub_i32 s100, s26, s100
	s_lshr_b32 s101, s100, 20
	s_lshl_b32 s100, s100, 12
	s_add_u32 s14, s14, s100
	s_addc_u32 s15, s15, s101
	global_load_dwordx4 v[192:195], v0, s[14:15]
	global_load_dwordx4 v[196:199], v0, s[14:15] offset:16
	global_load_dwordx4 v[200:203], v0, s[14:15] offset:2048
	global_load_dwordx4 v[208:211], v0, s[14:15] offset:2064
.Lmod_loop:
	v_lshlrev_b32_e32 v0, 3, v175
	v_and_b32_e32 v34, 0x1f8, v0
	v_lshlrev_b32_e32 v0, 2, v34
	s_add_i32 s6, s22, s13
	s_ashr_i32 s7, s6, 31
	s_add_i32 s10, s6, 1
	s_ashr_i32 s11, s10, 31
	s_ashr_i32 s12, s6, 11
	s_cmpk_gt_i32 s6, 0x3fff
	s_cselect_b32 s8, 8, s12
	s_mov_b32 s9, 0
	s_ashr_i32 s12, s10, 11
	s_cmpk_gt_i32 s10, 0x3fff
	s_cselect_b32 s0, 8, s12
	s_mov_b32 s1, 0
	s_waitcnt vmcnt(0)
	v_mov_b32_e32 v14, v176
	v_mov_b32_e32 v15, v177
	v_mov_b32_e32 v16, v178
	v_mov_b32_e32 v17, v179
	v_mov_b32_e32 v10, v180
	v_mov_b32_e32 v11, v181
	v_mov_b32_e32 v12, v182
	v_mov_b32_e32 v13, v183
	v_mov_b32_e32 v6, v184
	v_mov_b32_e32 v7, v185
	v_mov_b32_e32 v8, v186
	v_mov_b32_e32 v9, v187
	v_mov_b32_e32 v2, v188
	v_mov_b32_e32 v3, v189
	v_mov_b32_e32 v4, v190
	v_mov_b32_e32 v5, v191
	v_mov_b32_e32 v30, v192
	v_mov_b32_e32 v31, v193
	v_mov_b32_e32 v32, v194
	v_mov_b32_e32 v33, v195
	v_mov_b32_e32 v26, v196
	v_mov_b32_e32 v27, v197
	v_mov_b32_e32 v28, v198
	v_mov_b32_e32 v29, v199
	v_mov_b32_e32 v22, v200
	v_mov_b32_e32 v23, v201
	v_mov_b32_e32 v24, v202
	v_mov_b32_e32 v25, v203
	v_mov_b32_e32 v18, v208
	v_mov_b32_e32 v19, v209
	v_mov_b32_e32 v20, v210
	v_mov_b32_e32 v21, v211
	s_add_u32 s2, s8, s17
	s_addc_u32 s3, s9, s16
	s_mul_hi_u32 s8, s2, 0x3000
	s_mulk_i32 s3, 0x3000
	s_mulk_i32 s2, 0x3000
	s_add_i32 s3, s8, s3
	s_add_u32 s8, s28, s2
	s_addc_u32 s9, s29, s3
	s_lshl_b64 s[2:3], s[6:7], 11
	s_add_u32 s6, s96, s2
	s_addc_u32 s7, s97, s3
	s_add_u32 s0, s0, s17
	s_addc_u32 s2, s1, s16
	s_mul_hi_u32 s3, s0, 0x3000
	s_mulk_i32 s2, 0x3000
	s_mul_i32 s12, s0, 0x3000
	s_lshl_b64 s[0:1], s[10:11], 11
	s_add_i32 s3, s3, s2
	s_add_u32 s0, s96, s0
	s_addc_u32 s1, s97, s1
	s_add_u32 s2, s28, s12
	v_and_b32_e32 v35, 64, v207
	s_addc_u32 s3, s29, s3
	s_add_u32 s10, s8, 0x1000
	s_addc_u32 s11, s9, 0
	v_or_b32_e32 v98, 0x800, v0
	global_load_dwordx4 v[36:39], v0, s[4:5] offset:16
	global_load_dwordx4 v[40:43], v0, s[4:5]
	global_load_dwordx4 v[44:47], v0, s[4:5] offset:2064
	global_load_dwordx4 v[48:51], v0, s[4:5] offset:2048
	global_load_dwordx4 v[52:55], v0, s[10:11] offset:16
	global_load_dwordx4 v[56:59], v0, s[10:11]
	global_load_dwordx4 v[60:63], v98, s[10:11] offset:16
	global_load_dwordx4 v[64:67], v98, s[10:11]
	global_load_dwordx4 v[68:71], v0, s[8:9] offset:16
	global_load_dwordx4 v[72:75], v0, s[8:9]
	global_load_dwordx4 v[76:79], v0, s[8:9] offset:2064
	global_load_dwordx4 v[80:83], v0, s[8:9] offset:2048
	s_add_i32 s26, s23, 64
	s_cmpk_gt_i32 s26, 0xdf
	s_cselect_b32 s26, 0, 0x200
	s_add_i32 s26, s26, s22
	s_add_i32 s26, s26, s13
	s_cmpk_gt_i32 s26, 0x3fff
	s_cselect_b32 s14, s19, s21
	s_cselect_b32 s15, s18, s20
	s_cselect_b32 s100, 0x4000, 0
	s_sub_i32 s100, s26, s100
	s_lshr_b32 s101, s100, 20
	s_lshl_b32 s100, s100, 12
	s_add_u32 s14, s14, s100
	s_addc_u32 s15, s15, s101
	global_load_dwordx4 v[176:179], v0, s[14:15]
	global_load_dwordx4 v[180:183], v0, s[14:15] offset:16
	global_load_dwordx4 v[184:187], v0, s[14:15] offset:2048
	global_load_dwordx4 v[188:191], v0, s[14:15] offset:2064
	s_add_i32 s26, s26, 1
	s_cmpk_gt_i32 s26, 0x3fff
	s_cselect_b32 s14, s19, s21
	s_cselect_b32 s15, s18, s20
	s_cselect_b32 s100, 0x4000, 0
	s_sub_i32 s100, s26, s100
	s_lshr_b32 s101, s100, 20
	s_lshl_b32 s100, s100, 12
	s_add_u32 s14, s14, s100
	s_addc_u32 s15, s15, s101
	global_load_dwordx4 v[192:195], v0, s[14:15]
	global_load_dwordx4 v[196:199], v0, s[14:15] offset:16
	global_load_dwordx4 v[200:203], v0, s[14:15] offset:2048
	global_load_dwordx4 v[208:211], v0, s[14:15] offset:2064
	v_mov_b32_e32 v124, v15
	v_mov_b32_e32 v125, v11
	v_mov_b32_e32 v128, v7
	v_mov_b32_e32 v129, v3
	v_xor_b32_e32 v134, 1, v207
	v_add_u32_e32 v35, 64, v35
	v_mov_b32_e32 v122, v14
	v_mov_b32_e32 v123, v10
	v_mov_b32_e32 v126, v6
	v_mov_b32_e32 v127, v2
	v_xor_b32_e32 v135, 2, v207
	v_pk_mul_f32 v[124:125], v[124:125], v[124:125]
	v_pk_mul_f32 v[128:129], v[128:129], v[128:129]
	v_cmp_lt_i32_e32 vcc, v134, v35
	v_mov_b32_e32 v130, v16
	v_mov_b32_e32 v131, v12
	v_mov_b32_e32 v140, v8
	v_mov_b32_e32 v141, v4
	v_pk_fma_f32 v[132:133], v[122:123], v[122:123], v[124:125]
	v_pk_fma_f32 v[144:145], v[126:127], v[126:127], v[128:129]
	v_cndmask_b32_e32 v148, v207, v134, vcc
	v_cmp_lt_i32_e32 vcc, v135, v35
	v_mov_b32_e32 v138, v17
	v_mov_b32_e32 v139, v13
	v_mov_b32_e32 v142, v9
	v_mov_b32_e32 v143, v5
	v_cndmask_b32_e32 v149, v207, v135, vcc
	v_pk_fma_f32 v[146:147], v[130:131], v[130:131], v[132:133]
	v_pk_fma_f32 v[140:141], v[140:141], v[140:141], v[144:145]
	v_lshlrev_b32_e32 v99, 2, v148
	v_lshlrev_b32_e32 v100, 2, v149
	v_pk_fma_f32 v[84:85], v[138:139], v[138:139], v[146:147]
	v_pk_fma_f32 v[86:87], v[142:143], v[142:143], v[140:141]
	s_mov_b32 s8, 0x3a800000
	s_mov_b32 s10, 0x800000
	v_mov_b32_e32 v94, v23
	v_mov_b32_e32 v95, v19
	v_mov_b32_e32 v92, v22
	v_mov_b32_e32 v93, v18
	v_pk_mul_f32 v[94:95], v[94:95], v[94:95]
	v_mov_b32_e32 v88, v24
	v_mov_b32_e32 v89, v20
	v_pk_fma_f32 v[92:93], v[92:93], v[92:93], v[94:95]
	v_mov_b32_e32 v96, v31
	v_mov_b32_e32 v97, v27
	v_mov_b32_e32 v90, v25
	v_mov_b32_e32 v91, v21
	v_pk_fma_f32 v[88:89], v[88:89], v[88:89], v[92:93]
	v_mov_b32_e32 v94, v30
	v_mov_b32_e32 v95, v26
	v_pk_mul_f32 v[96:97], v[96:97], v[96:97]
	v_pk_fma_f32 v[88:89], v[90:91], v[90:91], v[88:89]
	v_mov_b32_e32 v90, v32
	v_mov_b32_e32 v91, v28
	v_pk_fma_f32 v[94:95], v[94:95], v[94:95], v[96:97]
	v_mov_b32_e32 v92, v33
	v_mov_b32_e32 v93, v29
	v_pk_fma_f32 v[90:91], v[90:91], v[90:91], v[94:95]
	s_waitcnt vmcnt(15)
	v_pk_add_f32 v[52:53], v[52:53], 1.0 op_sel_hi:[1,0]
	v_pk_fma_f32 v[90:91], v[92:93], v[92:93], v[90:91]
	v_mov_b32_e32 v93, v84
	v_mov_b32_e32 v92, v90
	v_mov_b32_e32 v84, v91
	v_pk_add_f32 v[84:85], v[92:93], v[84:85]
	v_mov_b32_e32 v90, v88
	v_mov_b32_e32 v91, v86
	v_pk_add_f32 v[84:85], v[84:85], v[90:91]
	v_mov_b32_e32 v86, v89
	v_pk_add_f32 v[84:85], v[84:85], v[86:87]
	ds_bpermute_b32 v87, v99, v85
	ds_bpermute_b32 v86, v99, v84
	v_xor_b32_e32 v88, 4, v207
	v_cmp_lt_i32_e32 vcc, v88, v35
	v_xor_b32_e32 v89, 8, v207
	s_waitcnt vmcnt(14)
	v_pk_add_f32 v[56:57], v[56:57], 1.0 op_sel_hi:[1,0]
	s_waitcnt lgkmcnt(0)
	v_pk_add_f32 v[84:85], v[84:85], v[86:87]
	ds_bpermute_b32 v87, v100, v85
	ds_bpermute_b32 v86, v100, v84
	v_cndmask_b32_e32 v88, v207, v88, vcc
	v_lshlrev_b32_e32 v88, 2, v88
	v_cmp_lt_i32_e32 vcc, v89, v35
	v_pk_add_f32 v[58:59], v[58:59], 1.0 op_sel_hi:[1,0]
	s_waitcnt lgkmcnt(0)
	v_pk_add_f32 v[84:85], v[84:85], v[86:87]
	ds_bpermute_b32 v87, v88, v85
	ds_bpermute_b32 v86, v88, v84
	v_cndmask_b32_e32 v89, v207, v89, vcc
	v_lshlrev_b32_e32 v89, 2, v89
	v_xor_b32_e32 v88, 16, v207
	v_cmp_lt_i32_e32 vcc, v88, v35
	s_waitcnt lgkmcnt(0)
	v_pk_add_f32 v[84:85], v[84:85], v[86:87]
	ds_bpermute_b32 v87, v89, v85
	ds_bpermute_b32 v86, v89, v84
	v_cndmask_b32_e32 v88, v207, v88, vcc
	v_lshlrev_b32_e32 v88, 2, v88
	v_xor_b32_e32 v89, 32, v207
	v_cmp_lt_i32_e32 vcc, v89, v35
	s_waitcnt lgkmcnt(0)
	v_pk_add_f32 v[84:85], v[84:85], v[86:87]
	ds_bpermute_b32 v87, v88, v85
	ds_bpermute_b32 v86, v88, v84
	v_cndmask_b32_e32 v35, v207, v89, vcc
	v_lshlrev_b32_e32 v35, 2, v35
	v_pk_add_f32 v[54:55], v[54:55], 1.0 op_sel_hi:[1,0]
	s_waitcnt vmcnt(12)
	v_pk_add_f32 v[64:65], v[64:65], 1.0 op_sel_hi:[1,0]
	s_waitcnt lgkmcnt(0)
	v_pk_add_f32 v[84:85], v[84:85], v[86:87]
	ds_bpermute_b32 v87, v35, v85
	ds_bpermute_b32 v86, v35, v84
	v_pk_add_f32 v[66:67], v[66:67], 1.0 op_sel_hi:[1,0]
	v_pk_add_f32 v[60:61], v[60:61], 1.0 op_sel_hi:[1,0]
	v_pk_add_f32 v[62:63], v[62:63], 1.0 op_sel_hi:[1,0]
	s_waitcnt lgkmcnt(0)
	v_pk_add_f32 v[84:85], v[84:85], v[86:87]
	s_nop 0
	v_pk_fma_f32 v[84:85], v[84:85], s[8:9], v[240:241] op_sel_hi:[1,0,0]
	s_add_u32 s8, s2, 0x1000
	v_mul_f32_e32 v35, 0x4b800000, v85
	v_cmp_gt_f32_e32 vcc, s10, v85
	s_addc_u32 s9, s3, 0
	s_add_i32 s23, s23, 64
	v_cndmask_b32_e32 v35, v85, v35, vcc
	v_rsq_f32_e32 v35, v35
	v_lshlrev_b32_e32 v85, 1, v34
	s_addk_i32 s22, 0x200
	s_cmpk_gt_i32 s23, 0xdf
	v_mul_f32_e32 v34, 0x45800000, v35
	v_cndmask_b32_e32 v34, v35, v34, vcc
	v_pk_mul_f32 v[14:15], v[14:15], v[34:35] op_sel_hi:[1,0]
	v_pk_mul_f32 v[16:17], v[16:17], v[34:35] op_sel_hi:[1,0]
	v_pk_mul_f32 v[10:11], v[10:11], v[34:35] op_sel_hi:[1,0]
	v_pk_mul_f32 v[12:13], v[12:13], v[34:35] op_sel_hi:[1,0]
	v_pk_mul_f32 v[14:15], v[40:41], v[14:15]
	v_pk_mul_f32 v[16:17], v[42:43], v[16:17]
	v_pk_mul_f32 v[10:11], v[10:11], v[36:37]
	v_pk_mul_f32 v[12:13], v[12:13], v[38:39]
	v_pk_mul_f32 v[6:7], v[6:7], v[34:35] op_sel_hi:[1,0]
	v_pk_mul_f32 v[8:9], v[8:9], v[34:35] op_sel_hi:[1,0]
	v_pk_mul_f32 v[2:3], v[2:3], v[34:35] op_sel_hi:[1,0]
	v_pk_mul_f32 v[4:5], v[4:5], v[34:35] op_sel_hi:[1,0]
	s_waitcnt vmcnt(10)
	v_pk_fma_f32 v[14:15], v[56:57], v[14:15], v[72:73]
	v_pk_fma_f32 v[16:17], v[58:59], v[16:17], v[74:75]
	v_pk_fma_f32 v[10:11], v[10:11], v[52:53], v[68:69]
	v_pk_fma_f32 v[12:13], v[12:13], v[54:55], v[70:71]
	v_pk_mul_f32 v[6:7], v[6:7], v[48:49]
	v_pk_mul_f32 v[8:9], v[8:9], v[50:51]
	v_pk_mul_f32 v[2:3], v[2:3], v[44:45]
	v_pk_mul_f32 v[4:5], v[4:5], v[46:47]
	v_cvt_pk_bf16_f32 v14, v14, v15
	v_cvt_pk_bf16_f32 v15, v16, v17
	v_cvt_pk_bf16_f32 v16, v10, v11
	v_cvt_pk_bf16_f32 v17, v12, v13
	s_waitcnt vmcnt(8)
	v_pk_fma_f32 v[6:7], v[6:7], v[64:65], v[80:81]
	v_pk_fma_f32 v[8:9], v[8:9], v[66:67], v[82:83]
	v_pk_fma_f32 v[2:3], v[2:3], v[60:61], v[76:77]
	v_pk_fma_f32 v[4:5], v[4:5], v[62:63], v[78:79]
	v_cvt_pk_bf16_f32 v6, v6, v7
	v_cvt_pk_bf16_f32 v7, v8, v9
	v_cvt_pk_bf16_f32 v8, v2, v3
	v_cvt_pk_bf16_f32 v9, v4, v5
	global_store_dwordx4 v85, v[14:17], s[6:7]
	global_store_dwordx4 v85, v[6:9], s[6:7] offset:1024
	v_mul_f32_e32 v0, 0x4b800000, v84
	v_cmp_gt_f32_e32 vcc, s10, v84
	v_cndmask_b32_e32 v0, v84, v0, vcc
	v_rsq_f32_e32 v0, v0
	v_mul_f32_e32 v86, 0x45800000, v0
	v_cndmask_b32_e32 v0, v0, v86, vcc
	v_pk_mul_f32 v[30:31], v[30:31], v[0:1] op_sel_hi:[1,0]
	v_pk_mul_f32 v[30:31], v[40:41], v[30:31]
	v_pk_fma_f32 v[30:31], v[56:57], v[30:31], v[72:73]
	v_pk_mul_f32 v[32:33], v[32:33], v[0:1] op_sel_hi:[1,0]
	v_pk_mul_f32 v[32:33], v[42:43], v[32:33]
	v_pk_fma_f32 v[32:33], v[58:59], v[32:33], v[74:75]
	v_pk_mul_f32 v[26:27], v[26:27], v[0:1] op_sel_hi:[1,0]
	v_pk_mul_f32 v[26:27], v[36:37], v[26:27]
	v_pk_fma_f32 v[26:27], v[52:53], v[26:27], v[68:69]
	v_pk_mul_f32 v[28:29], v[28:29], v[0:1] op_sel_hi:[1,0]
	v_pk_mul_f32 v[28:29], v[38:39], v[28:29]
	v_pk_fma_f32 v[28:29], v[54:55], v[28:29], v[70:71]
	v_cvt_pk_bf16_f32 v2, v30, v31
	v_cvt_pk_bf16_f32 v3, v32, v33
	v_cvt_pk_bf16_f32 v4, v26, v27
	v_cvt_pk_bf16_f32 v5, v28, v29
	global_store_dwordx4 v85, v[2:5], s[0:1]
	v_pk_mul_f32 v[22:23], v[22:23], v[0:1] op_sel_hi:[1,0]
	v_pk_mul_f32 v[22:23], v[48:49], v[22:23]
	v_pk_fma_f32 v[22:23], v[64:65], v[22:23], v[80:81]
	v_pk_mul_f32 v[24:25], v[24:25], v[0:1] op_sel_hi:[1,0]
	v_pk_mul_f32 v[24:25], v[50:51], v[24:25]
	v_pk_fma_f32 v[24:25], v[66:67], v[24:25], v[82:83]
	v_pk_mul_f32 v[18:19], v[18:19], v[0:1] op_sel_hi:[1,0]
	v_pk_mul_f32 v[18:19], v[44:45], v[18:19]
	v_pk_fma_f32 v[18:19], v[60:61], v[18:19], v[76:77]
	v_pk_mul_f32 v[20:21], v[20:21], v[0:1] op_sel_hi:[1,0]
	v_pk_mul_f32 v[20:21], v[46:47], v[20:21]
	v_pk_fma_f32 v[20:21], v[62:63], v[20:21], v[78:79]
	v_cvt_pk_bf16_f32 v6, v22, v23
	v_cvt_pk_bf16_f32 v7, v24, v25
	v_cvt_pk_bf16_f32 v8, v18, v19
	v_cvt_pk_bf16_f32 v9, v20, v21
	global_store_dwordx4 v85, v[6:9], s[0:1] offset:1024
	s_cbranch_scc1 .LBB0_760
	s_branch .Lmod_loop
